# GEMM K-loops (all three): LDS-DMA issue rebalanced 4 per phase with recounted vmcnt; iteration-0 phase-A wait relaxed to vmcnt(24) so it does not drain the previous tile's epilogue stores; sub4 epilog
# baseline (speedup 1.0000x reference)
; #define PG8_STAGE(bufoff, gbase, voff) do { _Pragma("unroll") for (int _i = 0; _i < 2; ++_i) \
;         __builtin_amdgcn_global_load_lds((const unsigned*)((const char*)(gbase) + (voff)[_i]), (LAS unsigned*)(lds + (bufoff) + ldsw + _i * 8192), 16, 0, 0); } while (0)
; #define PG8_LDA(dst, b, h) do { _Pragma("unroll") for (int m = 0; m < 4; ++m) _Pragma("unroll") for (int k = 0; k < 2; ++k) dst[m][k] = *(const LAS bf16x8*)(lds + PG8_SA(b, h) + aoff + m * 2048 + k * 1024); } while (0)
; #define PG8_LDB(dst, b, h) do { _Pragma("unroll") for (int n = 0; n < 2; ++n) _Pragma("unroll") for (int k = 0; k < 2; ++k) dst[n][k] = *(const LAS bf16x8*)(lds + PG8_SB(b, h) + boff + n * 2048 + k * 1024); } while (0)
; #define PG8_MMA(ai, bj, At, Bt) do { __builtin_amdgcn_s_setprio(1); _Pragma("unroll") for (int m = 0; m < 4; ++m) _Pragma("unroll") for (int n = 0; n < 2; ++n) _Pragma("unroll") for (int k = 0; k < 2; ++k) \
;         acc[ai][bj][m][n] = __builtin_amdgcn_mfma_f32_16x16x32_bf16(Bt[n][k], At[m][k], acc[ai][bj][m][n], 0, 0, 0); __builtin_amdgcn_s_setprio(0); } while (0)
; #define PG8_WAIT_V(n) asm volatile("s_waitcnt vmcnt(" #n ")" ::: "memory")
; #define PG8_WAIT_L(n) asm volatile("s_waitcnt lgkmcnt(" #n ")" ::: "memory")
; #define PG8_BAR __builtin_amdgcn_s_barrier()
; #define PG8_SCHED __builtin_amdgcn_sched_barrier(0)
; template <class Epi, bool ALIGN_EPI = true, class Sched = StaticOrder>
; __device__ __forceinline__ void gemm_phase(LAS unsigned char* lds, const Gemm g, const Sched& S, const Epi& E) {
;     ...
;             PG8_LDB(B0, 0, 0); PG8_LDB(B1, 0, 1); PG8_SCHED; PG8_LDA(At, 0, 0); PG8_STAGE(PG8_SA(1, 1), a1 + hstepA, voffA);
;             PG8_WAIT_V(8); PG8_WAIT_L(0); PG8_BAR; PG8_MMA(0, 0, At, B0); PG8_MMA(0, 1, At, B1); PG8_BAR; PG8_SCHED;
;             PG8_LDA(At, 0, 1); PG8_STAGE(PG8_SB(0, 0), b2, voffB); PG8_STAGE(PG8_SB(0, 1), b2 + hstepB, voffB); PG8_STAGE(PG8_SA(0, 0), a2, voffA);
;             PG8_WAIT_V(8); PG8_WAIT_L(0); PG8_BAR; PG8_MMA(1, 0, At, B0); PG8_MMA(1, 1, At, B1); PG8_BAR; PG8_SCHED;
.LBB0_43:
	s_add_u32 s6, s2, 0x100
	s_addc_u32 s7, s3, 0
	s_add_i32 s14, 0, 0x10000
	s_cmp_eq_u32 s52, 12
	s_cselect_b32 s11, s1, s7
	s_cselect_b32 s10, s0, s6
	s_cselect_b32 s9, s27, s51
	s_cselect_b32 s8, s49, s50
	s_add_i32 s15, 0, 0x14000
	v_add_u32_e32 v152, s14, v157
	v_add_u32_e32 v172, s15, v157
	ds_read_b128 v[130:133], v152
	ds_read_b128 v[134:137], v152 offset:1024
	ds_read_b128 v[148:151], v152 offset:2048
	ds_read_b128 v[152:155], v152 offset:3072
	ds_read_b128 v[160:163], v172
	ds_read_b128 v[164:167], v172 offset:1024
	ds_read_b128 v[168:171], v172 offset:2048
	ds_read_b128 v[172:175], v172 offset:3072
	s_add_u32 s100, s2, 0xffe10000
	s_addc_u32 s101, s3, -1
	v_lshl_add_u64 v[224:225], s[100:101], 0, v[144:145]
	s_mov_b32 m0, s44
	v_lshl_add_u64 v[218:219], s[100:101], 0, v[146:147]
	global_load_lds_dwordx4 v[224:225], off
	s_mov_b32 m0, s45
	s_nop 0
	global_load_lds_dwordx4 v[218:219], off
	v_lshl_add_u64 v[216:217], s[2:3], 0, v[144:145]
	s_add_i32 m0, s40, 0xc000
	ds_read_b128 v[176:179], v159
	ds_read_b128 v[180:183], v159 offset:1024
	ds_read_b128 v[184:187], v159 offset:2048
	ds_read_b128 v[188:191], v159 offset:3072
	ds_read_b128 v[192:195], v159 offset:4096
	ds_read_b128 v[196:199], v159 offset:5120
	ds_read_b128 v[200:203], v159 offset:6144
	ds_read_b128 v[204:207], v159 offset:7168
	global_load_lds_dwordx4 v[216:217], off
	v_lshl_add_u64 v[216:217], s[2:3], 0, v[146:147]
	s_add_i32 m0, s40, 0xe000
	s_nop 0
	global_load_lds_dwordx4 v[216:217], off
	s_cmp_lg_u32 s52, -2
	s_cbranch_scc1 .Lw8_s4p
	s_waitcnt vmcnt(24)
	s_branch .Lwj_s4p
.Lw8_s4p:
	s_waitcnt vmcnt(8)
.Lwj_s4p:
	s_waitcnt lgkmcnt(0)
	s_barrier
	s_setprio 1
	s_waitcnt lgkmcnt(0)
	v_mfma_f32_16x16x32_bf16 v[126:129], v[130:133], v[176:179], v[126:129]
	v_mfma_f32_16x16x32_bf16 v[122:125], v[148:151], v[176:179], v[122:125]
	v_mfma_f32_16x16x32_bf16 v[110:113], v[130:133], v[184:187], v[110:113]
	v_mfma_f32_16x16x32_bf16 v[106:109], v[148:151], v[184:187], v[106:109]
	v_mfma_f32_16x16x32_bf16 v[94:97], v[130:133], v[192:195], v[94:97]
	v_mfma_f32_16x16x32_bf16 v[90:93], v[148:151], v[192:195], v[90:93]
	v_mfma_f32_16x16x32_bf16 v[78:81], v[130:133], v[200:203], v[78:81]
	v_mfma_f32_16x16x32_bf16 v[74:77], v[148:151], v[200:203], v[74:77]
	v_mfma_f32_16x16x32_bf16 v[126:129], v[134:137], v[180:183], v[126:129]
	v_mfma_f32_16x16x32_bf16 v[122:125], v[152:155], v[180:183], v[122:125]
	v_mfma_f32_16x16x32_bf16 v[110:113], v[134:137], v[188:191], v[110:113]
	v_mfma_f32_16x16x32_bf16 v[106:109], v[152:155], v[188:191], v[106:109]
	v_mfma_f32_16x16x32_bf16 v[94:97], v[134:137], v[196:199], v[94:97]
	v_mfma_f32_16x16x32_bf16 v[90:93], v[152:155], v[196:199], v[90:93]
	v_mfma_f32_16x16x32_bf16 v[78:81], v[134:137], v[204:207], v[78:81]
	v_mfma_f32_16x16x32_bf16 v[74:77], v[152:155], v[204:207], v[74:77]
	s_setprio 0
	s_setprio 1
	v_mfma_f32_16x16x32_bf16 v[118:121], v[160:163], v[176:179], v[118:121]
	v_mfma_f32_16x16x32_bf16 v[114:117], v[168:171], v[176:179], v[114:117]
	v_mfma_f32_16x16x32_bf16 v[102:105], v[160:163], v[184:187], v[102:105]
	v_mfma_f32_16x16x32_bf16 v[98:101], v[168:171], v[184:187], v[98:101]
	v_mfma_f32_16x16x32_bf16 v[86:89], v[160:163], v[192:195], v[86:89]
	v_mfma_f32_16x16x32_bf16 v[82:85], v[168:171], v[192:195], v[82:85]
	v_mfma_f32_16x16x32_bf16 v[70:73], v[160:163], v[200:203], v[70:73]
	v_mfma_f32_16x16x32_bf16 v[66:69], v[168:171], v[200:203], v[66:69]
	v_mfma_f32_16x16x32_bf16 v[118:121], v[164:167], v[180:183], v[118:121]
	v_mfma_f32_16x16x32_bf16 v[114:117], v[172:175], v[180:183], v[114:117]
	v_mfma_f32_16x16x32_bf16 v[102:105], v[164:167], v[188:191], v[102:105]
	v_mfma_f32_16x16x32_bf16 v[98:101], v[172:175], v[188:191], v[98:101]
	v_mfma_f32_16x16x32_bf16 v[86:89], v[164:167], v[196:199], v[86:89]
	v_mfma_f32_16x16x32_bf16 v[82:85], v[172:175], v[196:199], v[82:85]
	v_mfma_f32_16x16x32_bf16 v[70:73], v[164:167], v[204:207], v[70:73]
	v_mfma_f32_16x16x32_bf16 v[66:69], v[172:175], v[204:207], v[66:69]
	s_setprio 0
	s_barrier
	s_add_i32 s2, s14, s39
	v_lshl_add_u64 v[216:217], s[8:9], 0, v[0:1]
	s_mov_b32 m0, s2
	ds_read_b128 v[176:179], v159 offset:16384
	ds_read_b128 v[180:183], v159 offset:17408
	ds_read_b128 v[184:187], v159 offset:18432
	ds_read_b128 v[188:191], v159 offset:19456
	ds_read_b128 v[192:195], v159 offset:20480
	ds_read_b128 v[196:199], v159 offset:21504
	ds_read_b128 v[200:203], v159 offset:22528
	ds_read_b128 v[204:207], v159 offset:23552
	global_load_lds_dwordx4 v[216:217], off
	s_add_i32 m0, s2, 0x2000
	s_add_u32 s2, s8, 0x80000
	v_lshl_add_u64 v[218:219], s[8:9], 0, v[142:143]
	s_addc_u32 s3, s9, 0
	s_add_i32 s14, s15, s39
	global_load_lds_dwordx4 v[218:219], off
	v_lshl_add_u64 v[220:221], s[2:3], 0, v[0:1]
	s_mov_b32 m0, s14
	v_lshl_add_u64 v[222:223], s[10:11], 0, v[140:141]
	global_load_lds_dwordx4 v[220:221], off
	v_lshl_add_u64 v[220:221], s[2:3], 0, v[142:143]
	s_add_i32 m0, s14, 0x2000
	s_nop 0
	global_load_lds_dwordx4 v[220:221], off
	v_lshl_add_u64 v[220:221], s[10:11], 0, v[138:139]
	s_waitcnt vmcnt(6)
	s_waitcnt lgkmcnt(0)
	s_barrier
; #define PG8_STAGE(bufoff, gbase, voff) do { _Pragma("unroll") for (int _i = 0; _i < 2; ++_i) \
;         __builtin_amdgcn_global_load_lds((const unsigned*)((const char*)(gbase) + (voff)[_i]), (LAS unsigned*)(lds + (bufoff) + ldsw + _i * 8192), 16, 0, 0); } while (0)
; #define PG8_LDA(dst, b, h) do { _Pragma("unroll") for (int m = 0; m < 4; ++m) _Pragma("unroll") for (int k = 0; k < 2; ++k) dst[m][k] = *(const LAS bf16x8*)(lds + PG8_SA(b, h) + aoff + m * 2048 + k * 1024); } while (0)
; #define PG8_LDB(dst, b, h) do { _Pragma("unroll") for (int n = 0; n < 2; ++n) _Pragma("unroll") for (int k = 0; k < 2; ++k) dst[n][k] = *(const LAS bf16x8*)(lds + PG8_SB(b, h) + boff + n * 2048 + k * 1024); } while (0)
; #define PG8_MMA(ai, bj, At, Bt) do { __builtin_amdgcn_s_setprio(1); _Pragma("unroll") for (int m = 0; m < 4; ++m) _Pragma("unroll") for (int n = 0; n < 2; ++n) _Pragma("unroll") for (int k = 0; k < 2; ++k) \
;         acc[ai][bj][m][n] = __builtin_amdgcn_mfma_f32_16x16x32_bf16(Bt[n][k], At[m][k], acc[ai][bj][m][n], 0, 0, 0); __builtin_amdgcn_s_setprio(0); } while (0)
; #define PG8_WAIT_V(n) asm volatile("s_waitcnt vmcnt(" #n ")" ::: "memory")
; #define PG8_WAIT_L(n) asm volatile("s_waitcnt lgkmcnt(" #n ")" ::: "memory")
; #define PG8_BAR __builtin_amdgcn_s_barrier()
; #define PG8_SCHED __builtin_amdgcn_sched_barrier(0)
; template <class Epi, bool ALIGN_EPI = true, class Sched = StaticOrder>
; __device__ __forceinline__ void gemm_phase(LAS unsigned char* lds, const Gemm g, const Sched& S, const Epi& E) {
;     ...
;             PG8_WAIT_V(8); PG8_WAIT_L(0); PG8_BAR; PG8_MMA(1, 0, At, B0); PG8_MMA(1, 1, At, B1); PG8_BAR; PG8_SCHED;
;             PG8_LDB(B0, 1, 0); PG8_LDB(B1, 1, 1); PG8_SCHED; PG8_LDA(At, 1, 0); PG8_STAGE(PG8_SA(0, 1), a2 + hstepA, voffA);
;             PG8_WAIT_V(8); PG8_WAIT_L(0); PG8_BAR; PG8_MMA(0, 0, At, B0); PG8_MMA(0, 1, At, B1); PG8_BAR; PG8_SCHED;
	s_setprio 1
	s_waitcnt lgkmcnt(0)
	v_mfma_f32_16x16x32_bf16 v[62:65], v[130:133], v[176:179], v[62:65]
	v_mfma_f32_16x16x32_bf16 v[58:61], v[148:151], v[176:179], v[58:61]
	v_mfma_f32_16x16x32_bf16 v[46:49], v[130:133], v[184:187], v[46:49]
	v_mfma_f32_16x16x32_bf16 v[42:45], v[148:151], v[184:187], v[42:45]
	v_mfma_f32_16x16x32_bf16 v[30:33], v[130:133], v[192:195], v[30:33]
	v_mfma_f32_16x16x32_bf16 v[26:29], v[148:151], v[192:195], v[26:29]
	v_mfma_f32_16x16x32_bf16 v[14:17], v[130:133], v[200:203], v[14:17]
	v_mfma_f32_16x16x32_bf16 v[10:13], v[148:151], v[200:203], v[10:13]
	v_mfma_f32_16x16x32_bf16 v[62:65], v[134:137], v[180:183], v[62:65]
	v_mfma_f32_16x16x32_bf16 v[58:61], v[152:155], v[180:183], v[58:61]
	v_mfma_f32_16x16x32_bf16 v[46:49], v[134:137], v[188:191], v[46:49]
	v_mfma_f32_16x16x32_bf16 v[42:45], v[152:155], v[188:191], v[42:45]
	v_mfma_f32_16x16x32_bf16 v[30:33], v[134:137], v[196:199], v[30:33]
	v_mfma_f32_16x16x32_bf16 v[26:29], v[152:155], v[196:199], v[26:29]
	v_mfma_f32_16x16x32_bf16 v[14:17], v[134:137], v[204:207], v[14:17]
	v_mfma_f32_16x16x32_bf16 v[10:13], v[152:155], v[204:207], v[10:13]
	s_setprio 0
	s_setprio 1
	v_mfma_f32_16x16x32_bf16 v[54:57], v[160:163], v[176:179], v[54:57]
	v_mfma_f32_16x16x32_bf16 v[50:53], v[168:171], v[176:179], v[50:53]
	v_mfma_f32_16x16x32_bf16 v[38:41], v[160:163], v[184:187], v[38:41]
	v_mfma_f32_16x16x32_bf16 v[34:37], v[168:171], v[184:187], v[34:37]
	v_mfma_f32_16x16x32_bf16 v[22:25], v[160:163], v[192:195], v[22:25]
	v_mfma_f32_16x16x32_bf16 v[18:21], v[168:171], v[192:195], v[18:21]
	v_mfma_f32_16x16x32_bf16 v[6:9], v[160:163], v[200:203], v[6:9]
	v_mfma_f32_16x16x32_bf16 v[2:5], v[168:171], v[200:203], v[2:5]
	v_mfma_f32_16x16x32_bf16 v[54:57], v[164:167], v[180:183], v[54:57]
	v_mfma_f32_16x16x32_bf16 v[50:53], v[172:175], v[180:183], v[50:53]
	v_mfma_f32_16x16x32_bf16 v[38:41], v[164:167], v[188:191], v[38:41]
	v_mfma_f32_16x16x32_bf16 v[34:37], v[172:175], v[188:191], v[34:37]
	v_mfma_f32_16x16x32_bf16 v[22:25], v[164:167], v[196:199], v[22:25]
	v_mfma_f32_16x16x32_bf16 v[18:21], v[172:175], v[196:199], v[18:21]
	v_mfma_f32_16x16x32_bf16 v[6:9], v[164:167], v[204:207], v[6:9]
	v_mfma_f32_16x16x32_bf16 v[2:5], v[172:175], v[204:207], v[2:5]
	s_setprio 0
	s_barrier
	s_mov_b32 m0, s40
	s_nop 0
	global_load_lds_dwordx4 v[220:221], off
	s_mov_b32 m0, s41
	s_nop 0
	global_load_lds_dwordx4 v[222:223], off
	s_add_i32 s14, 0, 0x18000
	s_add_i32 s15, 0, 0x1c000
	v_add_u32_e32 v152, s14, v157
	v_add_u32_e32 v172, s15, v157
	ds_read_b128 v[130:133], v152
	ds_read_b128 v[134:137], v152 offset:1024
	ds_read_b128 v[148:151], v152 offset:2048
	ds_read_b128 v[152:155], v152 offset:3072
	ds_read_b128 v[160:163], v172
	ds_read_b128 v[164:167], v172 offset:1024
	ds_read_b128 v[168:171], v172 offset:2048
	ds_read_b128 v[172:175], v172 offset:3072
	s_add_u32 s2, s10, 0x1f0000
	s_addc_u32 s3, s11, 0
	s_mov_b32 m0, s42
	v_lshl_add_u64 v[224:225], s[2:3], 0, v[138:139]
	ds_read_b128 v[176:179], v159 offset:32768
	ds_read_b128 v[180:183], v159 offset:33792
	ds_read_b128 v[184:187], v159 offset:34816
	ds_read_b128 v[188:191], v159 offset:35840
	ds_read_b128 v[192:195], v159 offset:36864
	ds_read_b128 v[196:199], v159 offset:37888
	ds_read_b128 v[200:203], v159 offset:38912
	ds_read_b128 v[204:207], v159 offset:39936
	global_load_lds_dwordx4 v[224:225], off
	v_lshl_add_u64 v[224:225], s[2:3], 0, v[140:141]
	s_mov_b32 m0, s43
	s_nop 0
	global_load_lds_dwordx4 v[224:225], off
	s_waitcnt vmcnt(8)
	s_waitcnt lgkmcnt(0)
	s_barrier
; #define PG8_STAGE(bufoff, gbase, voff) do { _Pragma("unroll") for (int _i = 0; _i < 2; ++_i) \
;         __builtin_amdgcn_global_load_lds((const unsigned*)((const char*)(gbase) + (voff)[_i]), (LAS unsigned*)(lds + (bufoff) + ldsw + _i * 8192), 16, 0, 0); } while (0)
; #define PG8_LDA(dst, b, h) do { _Pragma("unroll") for (int m = 0; m < 4; ++m) _Pragma("unroll") for (int k = 0; k < 2; ++k) dst[m][k] = *(const LAS bf16x8*)(lds + PG8_SA(b, h) + aoff + m * 2048 + k * 1024); } while (0)
; #define PG8_MMA(ai, bj, At, Bt) do { __builtin_amdgcn_s_setprio(1); _Pragma("unroll") for (int m = 0; m < 4; ++m) _Pragma("unroll") for (int n = 0; n < 2; ++n) _Pragma("unroll") for (int k = 0; k < 2; ++k) \
;         acc[ai][bj][m][n] = __builtin_amdgcn_mfma_f32_16x16x32_bf16(Bt[n][k], At[m][k], acc[ai][bj][m][n], 0, 0, 0); __builtin_amdgcn_s_setprio(0); } while (0)
; #define PG8_WAIT_V(n) asm volatile("s_waitcnt vmcnt(" #n ")" ::: "memory")
; #define PG8_WAIT_L(n) asm volatile("s_waitcnt lgkmcnt(" #n ")" ::: "memory")
; #define PG8_BAR __builtin_amdgcn_s_barrier()
; #define PG8_SCHED __builtin_amdgcn_sched_barrier(0)
; template <class Epi, bool ALIGN_EPI = true, class Sched = StaticOrder>
; __device__ __forceinline__ void gemm_phase(LAS unsigned char* lds, const Gemm g, const Sched& S, const Epi& E) {
;     ...
;             PG8_WAIT_V(8); PG8_WAIT_L(0); PG8_BAR; PG8_MMA(0, 0, At, B0); PG8_MMA(0, 1, At, B1); PG8_BAR; PG8_SCHED;
;             PG8_LDA(At, 1, 1); PG8_STAGE(PG8_SB(1, 0), b3, voffB); PG8_STAGE(PG8_SB(1, 1), b3 + hstepB, voffB); PG8_STAGE(PG8_SA(1, 0), a3, voffA);
;             PG8_WAIT_V(8); PG8_WAIT_L(0); PG8_BAR; PG8_MMA(1, 0, At, B0); PG8_MMA(1, 1, At, B1); PG8_BAR; PG8_SCHED;
;         }
;         if constexpr (Epi::HAS_PRE) { if (has_next) E.pre(nxt, (ui + 1) & 1); }
;         if constexpr (ALIGN_EPI) { if (wr == 0) PG8_BAR; }
	s_setprio 1
	s_waitcnt lgkmcnt(0)
	v_mfma_f32_16x16x32_bf16 v[126:129], v[130:133], v[176:179], v[126:129]
	v_mfma_f32_16x16x32_bf16 v[122:125], v[148:151], v[176:179], v[122:125]
	v_mfma_f32_16x16x32_bf16 v[110:113], v[130:133], v[184:187], v[110:113]
	v_mfma_f32_16x16x32_bf16 v[106:109], v[148:151], v[184:187], v[106:109]
	v_mfma_f32_16x16x32_bf16 v[94:97], v[130:133], v[192:195], v[94:97]
	v_mfma_f32_16x16x32_bf16 v[90:93], v[148:151], v[192:195], v[90:93]
	v_mfma_f32_16x16x32_bf16 v[78:81], v[130:133], v[200:203], v[78:81]
	v_mfma_f32_16x16x32_bf16 v[74:77], v[148:151], v[200:203], v[74:77]
	v_mfma_f32_16x16x32_bf16 v[126:129], v[134:137], v[180:183], v[126:129]
	v_mfma_f32_16x16x32_bf16 v[122:125], v[152:155], v[180:183], v[122:125]
	v_mfma_f32_16x16x32_bf16 v[110:113], v[134:137], v[188:191], v[110:113]
	v_mfma_f32_16x16x32_bf16 v[106:109], v[152:155], v[188:191], v[106:109]
	v_mfma_f32_16x16x32_bf16 v[94:97], v[134:137], v[196:199], v[94:97]
	v_mfma_f32_16x16x32_bf16 v[90:93], v[152:155], v[196:199], v[90:93]
	v_mfma_f32_16x16x32_bf16 v[78:81], v[134:137], v[204:207], v[78:81]
	v_mfma_f32_16x16x32_bf16 v[74:77], v[152:155], v[204:207], v[74:77]
	s_setprio 0
	s_setprio 1
	v_mfma_f32_16x16x32_bf16 v[118:121], v[160:163], v[176:179], v[118:121]
	v_mfma_f32_16x16x32_bf16 v[114:117], v[168:171], v[176:179], v[114:117]
	v_mfma_f32_16x16x32_bf16 v[102:105], v[160:163], v[184:187], v[102:105]
	v_mfma_f32_16x16x32_bf16 v[98:101], v[168:171], v[184:187], v[98:101]
	v_mfma_f32_16x16x32_bf16 v[86:89], v[160:163], v[192:195], v[86:89]
	v_mfma_f32_16x16x32_bf16 v[82:85], v[168:171], v[192:195], v[82:85]
	v_mfma_f32_16x16x32_bf16 v[70:73], v[160:163], v[200:203], v[70:73]
	v_mfma_f32_16x16x32_bf16 v[66:69], v[168:171], v[200:203], v[66:69]
	v_mfma_f32_16x16x32_bf16 v[118:121], v[164:167], v[180:183], v[118:121]
	v_mfma_f32_16x16x32_bf16 v[114:117], v[172:175], v[180:183], v[114:117]
	v_mfma_f32_16x16x32_bf16 v[102:105], v[164:167], v[188:191], v[102:105]
	v_mfma_f32_16x16x32_bf16 v[98:101], v[172:175], v[188:191], v[98:101]
	v_mfma_f32_16x16x32_bf16 v[86:89], v[164:167], v[196:199], v[86:89]
	v_mfma_f32_16x16x32_bf16 v[82:85], v[172:175], v[196:199], v[82:85]
	v_mfma_f32_16x16x32_bf16 v[70:73], v[164:167], v[204:207], v[70:73]
	v_mfma_f32_16x16x32_bf16 v[66:69], v[172:175], v[204:207], v[66:69]
	s_setprio 0
	s_barrier
	s_add_i32 s2, s14, s39
	v_lshl_add_u64 v[216:217], v[216:217], 0, s[70:71]
	s_mov_b32 m0, s2
	ds_read_b128 v[176:179], v159 offset:49152
	ds_read_b128 v[180:183], v159 offset:50176
	ds_read_b128 v[184:187], v159 offset:51200
	ds_read_b128 v[188:191], v159 offset:52224
	ds_read_b128 v[192:195], v159 offset:53248
	ds_read_b128 v[196:199], v159 offset:54272
	ds_read_b128 v[200:203], v159 offset:55296
	ds_read_b128 v[204:207], v159 offset:56320
	global_load_lds_dwordx4 v[216:217], off
	s_add_i32 m0, s2, 0x2000
	s_add_u32 s2, s8, 0x80080
	v_lshl_add_u64 v[216:217], v[218:219], 0, s[70:71]
	s_addc_u32 s3, s9, 0
	s_add_i32 s8, s15, s39
	global_load_lds_dwordx4 v[216:217], off
	v_lshl_add_u64 v[216:217], s[2:3], 0, v[0:1]
	s_mov_b32 m0, s8
	s_nop 0
	global_load_lds_dwordx4 v[216:217], off
	v_lshl_add_u64 v[216:217], s[2:3], 0, v[142:143]
	s_add_i32 m0, s8, 0x2000
	s_nop 0
	global_load_lds_dwordx4 v[216:217], off
	s_waitcnt vmcnt(6)
	s_waitcnt lgkmcnt(0)
	s_barrier
	s_setprio 1
	s_waitcnt lgkmcnt(0)
	v_mfma_f32_16x16x32_bf16 v[62:65], v[130:133], v[176:179], v[62:65]
	v_mfma_f32_16x16x32_bf16 v[58:61], v[148:151], v[176:179], v[58:61]
	v_mfma_f32_16x16x32_bf16 v[46:49], v[130:133], v[184:187], v[46:49]
	v_mfma_f32_16x16x32_bf16 v[42:45], v[148:151], v[184:187], v[42:45]
	v_mfma_f32_16x16x32_bf16 v[30:33], v[130:133], v[192:195], v[30:33]
	v_mfma_f32_16x16x32_bf16 v[26:29], v[148:151], v[192:195], v[26:29]
	v_mfma_f32_16x16x32_bf16 v[14:17], v[130:133], v[200:203], v[14:17]
	v_mfma_f32_16x16x32_bf16 v[10:13], v[148:151], v[200:203], v[10:13]
	v_mfma_f32_16x16x32_bf16 v[62:65], v[134:137], v[180:183], v[62:65]
	v_mfma_f32_16x16x32_bf16 v[58:61], v[152:155], v[180:183], v[58:61]
	v_mfma_f32_16x16x32_bf16 v[46:49], v[134:137], v[188:191], v[46:49]
	v_mfma_f32_16x16x32_bf16 v[42:45], v[152:155], v[188:191], v[42:45]
	v_mfma_f32_16x16x32_bf16 v[30:33], v[134:137], v[196:199], v[30:33]
	v_mfma_f32_16x16x32_bf16 v[26:29], v[152:155], v[196:199], v[26:29]
	v_mfma_f32_16x16x32_bf16 v[14:17], v[134:137], v[204:207], v[14:17]
	v_mfma_f32_16x16x32_bf16 v[10:13], v[152:155], v[204:207], v[10:13]
	s_setprio 0
	s_setprio 1
	v_mfma_f32_16x16x32_bf16 v[54:57], v[160:163], v[176:179], v[54:57]
	v_mfma_f32_16x16x32_bf16 v[50:53], v[168:171], v[176:179], v[50:53]
	v_mfma_f32_16x16x32_bf16 v[38:41], v[160:163], v[184:187], v[38:41]
	v_mfma_f32_16x16x32_bf16 v[34:37], v[168:171], v[184:187], v[34:37]
	v_mfma_f32_16x16x32_bf16 v[22:25], v[160:163], v[192:195], v[22:25]
	v_mfma_f32_16x16x32_bf16 v[18:21], v[168:171], v[192:195], v[18:21]
	v_mfma_f32_16x16x32_bf16 v[6:9], v[160:163], v[200:203], v[6:9]
	v_mfma_f32_16x16x32_bf16 v[2:5], v[168:171], v[200:203], v[2:5]
	v_mfma_f32_16x16x32_bf16 v[54:57], v[164:167], v[180:183], v[54:57]
	v_mfma_f32_16x16x32_bf16 v[50:53], v[172:175], v[180:183], v[50:53]
	v_mfma_f32_16x16x32_bf16 v[38:41], v[164:167], v[188:191], v[38:41]
	v_mfma_f32_16x16x32_bf16 v[34:37], v[172:175], v[188:191], v[34:37]
	v_mfma_f32_16x16x32_bf16 v[22:25], v[164:167], v[196:199], v[22:25]
	v_mfma_f32_16x16x32_bf16 v[18:21], v[172:175], v[196:199], v[18:21]
	v_mfma_f32_16x16x32_bf16 v[6:9], v[164:167], v[204:207], v[6:9]
	v_mfma_f32_16x16x32_bf16 v[2:5], v[172:175], v[204:207], v[2:5]
	s_setprio 0
	s_barrier
	s_add_i32 s52, s52, 2
	s_add_u32 s50, s50, 0x100
	s_addc_u32 s51, s51, 0
	s_cmp_gt_u32 s52, 13
	s_mov_b64 s[2:3], s[6:7]
	s_cbranch_scc0 .LBB0_43
	s_and_b64 vcc, exec, s[64:65]
	s_cbranch_vccz .LBB0_46
	s_barrier

; #define PG8_STAGE(bufoff, gbase, voff) do { _Pragma("unroll") for (int _i = 0; _i < 2; ++_i) \
;         __builtin_amdgcn_global_load_lds((const unsigned*)((const char*)(gbase) + (voff)[_i]), (LAS unsigned*)(lds + (bufoff) + ldsw + _i * 8192), 16, 0, 0); } while (0)
; #define PG8_LDA(dst, b, h) do { _Pragma("unroll") for (int m = 0; m < 4; ++m) _Pragma("unroll") for (int k = 0; k < 2; ++k) dst[m][k] = *(const LAS bf16x8*)(lds + PG8_SA(b, h) + aoff + m * 2048 + k * 1024); } while (0)
; #define PG8_LDB(dst, b, h) do { _Pragma("unroll") for (int n = 0; n < 2; ++n) _Pragma("unroll") for (int k = 0; k < 2; ++k) dst[n][k] = *(const LAS bf16x8*)(lds + PG8_SB(b, h) + boff + n * 2048 + k * 1024); } while (0)
; #define PG8_MMA(ai, bj, At, Bt) do { __builtin_amdgcn_s_setprio(1); _Pragma("unroll") for (int m = 0; m < 4; ++m) _Pragma("unroll") for (int n = 0; n < 2; ++n) _Pragma("unroll") for (int k = 0; k < 2; ++k) \
;         acc[ai][bj][m][n] = __builtin_amdgcn_mfma_f32_16x16x32_bf16(Bt[n][k], At[m][k], acc[ai][bj][m][n], 0, 0, 0); __builtin_amdgcn_s_setprio(0); } while (0)
; #define PG8_WAIT_V(n) asm volatile("s_waitcnt vmcnt(" #n ")" ::: "memory")
; #define PG8_WAIT_L(n) asm volatile("s_waitcnt lgkmcnt(" #n ")" ::: "memory")
; #define PG8_BAR __builtin_amdgcn_s_barrier()
; #define PG8_SCHED __builtin_amdgcn_sched_barrier(0)
; template <class Epi, bool ALIGN_EPI = true, class Sched = StaticOrder>
; __device__ __forceinline__ void gemm_phase(LAS unsigned char* lds, const Gemm g, const Sched& S, const Epi& E) {
;     ...
;             PG8_LDB(B0, 0, 0); PG8_LDB(B1, 0, 1); PG8_SCHED; PG8_LDA(At, 0, 0); PG8_STAGE(PG8_SA(1, 1), a1 + hstepA, voffA);
;             PG8_WAIT_V(8); PG8_WAIT_L(0); PG8_BAR; PG8_MMA(0, 0, At, B0); PG8_MMA(0, 1, At, B1); PG8_BAR; PG8_SCHED;
.LBB0_338:
	s_add_u32 s0, s62, 0x100
	s_addc_u32 s1, s63, 0
	s_add_i32 s51, 0, 0x10000
	s_cmp_eq_u32 s50, 12
	s_cselect_b32 s37, s57, s1
	s_cselect_b32 s36, s56, s0
	s_cselect_b32 s65, s13, s49
	s_cselect_b32 s64, s47, s48
	s_add_i32 s55, 0, 0x14000
	v_add_u32_e32 v156, s51, v145
	v_add_u32_e32 v172, s55, v145
	ds_read_b128 v[140:143], v156
	ds_read_b128 v[148:151], v156 offset:1024
	ds_read_b128 v[152:155], v156 offset:2048
	ds_read_b128 v[156:159], v156 offset:3072
	ds_read_b128 v[160:163], v172
	ds_read_b128 v[164:167], v172 offset:1024
	ds_read_b128 v[168:171], v172 offset:2048
	ds_read_b128 v[172:175], v172 offset:3072
	s_add_u32 s100, s62, 0xffe10000
	s_addc_u32 s101, s63, -1
	v_lshl_add_u64 v[224:225], s[100:101], 0, v[136:137]
	s_mov_b32 m0, s42
	v_lshl_add_u64 v[218:219], s[100:101], 0, v[138:139]
	global_load_lds_dwordx4 v[224:225], off
	s_mov_b32 m0, s43
	s_nop 0
	global_load_lds_dwordx4 v[218:219], off
	v_lshl_add_u64 v[216:217], s[62:63], 0, v[136:137]
	s_add_i32 m0, s26, 0xc000
	ds_read_b128 v[176:179], v147
	ds_read_b128 v[180:183], v147 offset:1024
	ds_read_b128 v[184:187], v147 offset:2048
	ds_read_b128 v[188:191], v147 offset:3072
	ds_read_b128 v[192:195], v147 offset:4096
	ds_read_b128 v[196:199], v147 offset:5120
	ds_read_b128 v[200:203], v147 offset:6144
	ds_read_b128 v[204:207], v147 offset:7168
	global_load_lds_dwordx4 v[216:217], off
	v_lshl_add_u64 v[216:217], s[62:63], 0, v[138:139]
	s_add_i32 m0, s26, 0xe000
	s_nop 0
	global_load_lds_dwordx4 v[216:217], off
	s_cmp_lg_u32 s50, -2
	s_cbranch_scc1 .Lw8_s5p
	s_waitcnt vmcnt(63)
	s_branch .Lwj_s5p

; #define PG8_STAGE(bufoff, gbase, voff) do { _Pragma("unroll") for (int _i = 0; _i < 2; ++_i) \
;         __builtin_amdgcn_global_load_lds((const unsigned*)((const char*)(gbase) + (voff)[_i]), (LAS unsigned*)(lds + (bufoff) + ldsw + _i * 8192), 16, 0, 0); } while (0)
; #define PG8_LDA(dst, b, h) do { _Pragma("unroll") for (int m = 0; m < 4; ++m) _Pragma("unroll") for (int k = 0; k < 2; ++k) dst[m][k] = *(const LAS bf16x8*)(lds + PG8_SA(b, h) + aoff + m * 2048 + k * 1024); } while (0)
; #define PG8_MMA(ai, bj, At, Bt) do { __builtin_amdgcn_s_setprio(1); _Pragma("unroll") for (int m = 0; m < 4; ++m) _Pragma("unroll") for (int n = 0; n < 2; ++n) _Pragma("unroll") for (int k = 0; k < 2; ++k) \
;         acc[ai][bj][m][n] = __builtin_amdgcn_mfma_f32_16x16x32_bf16(Bt[n][k], At[m][k], acc[ai][bj][m][n], 0, 0, 0); __builtin_amdgcn_s_setprio(0); } while (0)
; #define PG8_WAIT_V(n) asm volatile("s_waitcnt vmcnt(" #n ")" ::: "memory")
; #define PG8_WAIT_L(n) asm volatile("s_waitcnt lgkmcnt(" #n ")" ::: "memory")
; #define PG8_BAR __builtin_amdgcn_s_barrier()
; #define PG8_SCHED __builtin_amdgcn_sched_barrier(0)
; template <class Epi, bool ALIGN_EPI = true, class Sched = StaticOrder>
; __device__ __forceinline__ void gemm_phase(LAS unsigned char* lds, const Gemm g, const Sched& S, const Epi& E) {
;     ...
;             PG8_WAIT_V(8); PG8_WAIT_L(0); PG8_BAR; PG8_MMA(0, 0, At, B0); PG8_MMA(0, 1, At, B1); PG8_BAR; PG8_SCHED;
;             PG8_LDA(At, 0, 1); PG8_STAGE(PG8_SB(0, 0), b2, voffB); PG8_STAGE(PG8_SB(0, 1), b2 + hstepB, voffB); PG8_STAGE(PG8_SA(0, 0), a2, voffA);
;             PG8_WAIT_V(8); PG8_WAIT_L(0); PG8_BAR; PG8_MMA(1, 0, At, B0); PG8_MMA(1, 1, At, B1); PG8_BAR; PG8_SCHED;
.Lwj_s5p:
	s_waitcnt lgkmcnt(0)
	s_barrier
	s_setprio 1
	s_waitcnt lgkmcnt(0)
	v_mfma_f32_16x16x32_bf16 v[126:129], v[140:143], v[176:179], v[126:129]
	v_mfma_f32_16x16x32_bf16 v[122:125], v[152:155], v[176:179], v[122:125]
	v_mfma_f32_16x16x32_bf16 v[110:113], v[140:143], v[184:187], v[110:113]
	v_mfma_f32_16x16x32_bf16 v[106:109], v[152:155], v[184:187], v[106:109]
	v_mfma_f32_16x16x32_bf16 v[94:97], v[140:143], v[192:195], v[94:97]
	v_mfma_f32_16x16x32_bf16 v[90:93], v[152:155], v[192:195], v[90:93]
	v_mfma_f32_16x16x32_bf16 v[78:81], v[140:143], v[200:203], v[78:81]
	v_mfma_f32_16x16x32_bf16 v[74:77], v[152:155], v[200:203], v[74:77]
	v_mfma_f32_16x16x32_bf16 v[126:129], v[148:151], v[180:183], v[126:129]
	v_mfma_f32_16x16x32_bf16 v[122:125], v[156:159], v[180:183], v[122:125]
	v_mfma_f32_16x16x32_bf16 v[110:113], v[148:151], v[188:191], v[110:113]
	v_mfma_f32_16x16x32_bf16 v[106:109], v[156:159], v[188:191], v[106:109]
	v_mfma_f32_16x16x32_bf16 v[94:97], v[148:151], v[196:199], v[94:97]
	v_mfma_f32_16x16x32_bf16 v[90:93], v[156:159], v[196:199], v[90:93]
	v_mfma_f32_16x16x32_bf16 v[78:81], v[148:151], v[204:207], v[78:81]
	v_mfma_f32_16x16x32_bf16 v[74:77], v[156:159], v[204:207], v[74:77]
	s_setprio 0
	s_setprio 1
	v_mfma_f32_16x16x32_bf16 v[118:121], v[160:163], v[176:179], v[118:121]
	v_mfma_f32_16x16x32_bf16 v[114:117], v[168:171], v[176:179], v[114:117]
	v_mfma_f32_16x16x32_bf16 v[102:105], v[160:163], v[184:187], v[102:105]
	v_mfma_f32_16x16x32_bf16 v[98:101], v[168:171], v[184:187], v[98:101]
	v_mfma_f32_16x16x32_bf16 v[86:89], v[160:163], v[192:195], v[86:89]
	v_mfma_f32_16x16x32_bf16 v[82:85], v[168:171], v[192:195], v[82:85]
	v_mfma_f32_16x16x32_bf16 v[70:73], v[160:163], v[200:203], v[70:73]
	v_mfma_f32_16x16x32_bf16 v[66:69], v[168:171], v[200:203], v[66:69]
	v_mfma_f32_16x16x32_bf16 v[118:121], v[164:167], v[180:183], v[118:121]
	v_mfma_f32_16x16x32_bf16 v[114:117], v[172:175], v[180:183], v[114:117]
	v_mfma_f32_16x16x32_bf16 v[102:105], v[164:167], v[188:191], v[102:105]
	v_mfma_f32_16x16x32_bf16 v[98:101], v[172:175], v[188:191], v[98:101]
	v_mfma_f32_16x16x32_bf16 v[86:89], v[164:167], v[196:199], v[86:89]
	v_mfma_f32_16x16x32_bf16 v[82:85], v[172:175], v[196:199], v[82:85]
	v_mfma_f32_16x16x32_bf16 v[70:73], v[164:167], v[204:207], v[70:73]
	v_mfma_f32_16x16x32_bf16 v[66:69], v[172:175], v[204:207], v[66:69]
	s_setprio 0
	s_barrier
	s_add_i32 s51, s51, s25
	v_lshl_add_u64 v[216:217], s[64:65], 0, v[0:1]
	s_mov_b32 m0, s51
	ds_read_b128 v[176:179], v147 offset:16384
	ds_read_b128 v[180:183], v147 offset:17408
	ds_read_b128 v[184:187], v147 offset:18432
	ds_read_b128 v[188:191], v147 offset:19456
	ds_read_b128 v[192:195], v147 offset:20480
	ds_read_b128 v[196:199], v147 offset:21504
	ds_read_b128 v[200:203], v147 offset:22528
	ds_read_b128 v[204:207], v147 offset:23552
	global_load_lds_dwordx4 v[216:217], off
	s_add_i32 m0, s51, 0x2000
	s_add_u32 s52, s64, 0x40000
	v_lshl_add_u64 v[218:219], s[64:65], 0, v[134:135]
	s_addc_u32 s53, s65, 0
	s_add_i32 s51, s55, s25
	global_load_lds_dwordx4 v[218:219], off
	v_lshl_add_u64 v[220:221], s[52:53], 0, v[0:1]
	s_mov_b32 m0, s51
	v_lshl_add_u64 v[222:223], s[36:37], 0, v[132:133]
	global_load_lds_dwordx4 v[220:221], off
	v_lshl_add_u64 v[220:221], s[52:53], 0, v[134:135]
	s_add_i32 m0, s51, 0x2000
	s_nop 0
	global_load_lds_dwordx4 v[220:221], off
	v_lshl_add_u64 v[220:221], s[36:37], 0, v[130:131]
	s_waitcnt vmcnt(6)
	s_waitcnt lgkmcnt(0)
	s_barrier
	s_setprio 1
	s_waitcnt lgkmcnt(0)
	v_mfma_f32_16x16x32_bf16 v[62:65], v[140:143], v[176:179], v[62:65]
	v_mfma_f32_16x16x32_bf16 v[58:61], v[152:155], v[176:179], v[58:61]
	v_mfma_f32_16x16x32_bf16 v[46:49], v[140:143], v[184:187], v[46:49]
	v_mfma_f32_16x16x32_bf16 v[42:45], v[152:155], v[184:187], v[42:45]
	v_mfma_f32_16x16x32_bf16 v[30:33], v[140:143], v[192:195], v[30:33]
	v_mfma_f32_16x16x32_bf16 v[26:29], v[152:155], v[192:195], v[26:29]
	v_mfma_f32_16x16x32_bf16 v[14:17], v[140:143], v[200:203], v[14:17]
	v_mfma_f32_16x16x32_bf16 v[10:13], v[152:155], v[200:203], v[10:13]
	v_mfma_f32_16x16x32_bf16 v[62:65], v[148:151], v[180:183], v[62:65]
	v_mfma_f32_16x16x32_bf16 v[58:61], v[156:159], v[180:183], v[58:61]
	v_mfma_f32_16x16x32_bf16 v[46:49], v[148:151], v[188:191], v[46:49]
	v_mfma_f32_16x16x32_bf16 v[42:45], v[156:159], v[188:191], v[42:45]
	v_mfma_f32_16x16x32_bf16 v[30:33], v[148:151], v[196:199], v[30:33]
	v_mfma_f32_16x16x32_bf16 v[26:29], v[156:159], v[196:199], v[26:29]
	v_mfma_f32_16x16x32_bf16 v[14:17], v[148:151], v[204:207], v[14:17]
	v_mfma_f32_16x16x32_bf16 v[10:13], v[156:159], v[204:207], v[10:13]
	s_setprio 0
	s_setprio 1
	v_mfma_f32_16x16x32_bf16 v[54:57], v[160:163], v[176:179], v[54:57]
	v_mfma_f32_16x16x32_bf16 v[50:53], v[168:171], v[176:179], v[50:53]
	v_mfma_f32_16x16x32_bf16 v[38:41], v[160:163], v[184:187], v[38:41]
	v_mfma_f32_16x16x32_bf16 v[34:37], v[168:171], v[184:187], v[34:37]
	v_mfma_f32_16x16x32_bf16 v[22:25], v[160:163], v[192:195], v[22:25]
	v_mfma_f32_16x16x32_bf16 v[18:21], v[168:171], v[192:195], v[18:21]
	v_mfma_f32_16x16x32_bf16 v[6:9], v[160:163], v[200:203], v[6:9]
	v_mfma_f32_16x16x32_bf16 v[2:5], v[168:171], v[200:203], v[2:5]
	v_mfma_f32_16x16x32_bf16 v[54:57], v[164:167], v[180:183], v[54:57]
	v_mfma_f32_16x16x32_bf16 v[50:53], v[172:175], v[180:183], v[50:53]
	v_mfma_f32_16x16x32_bf16 v[38:41], v[164:167], v[188:191], v[38:41]
	v_mfma_f32_16x16x32_bf16 v[34:37], v[172:175], v[188:191], v[34:37]
	v_mfma_f32_16x16x32_bf16 v[22:25], v[164:167], v[196:199], v[22:25]
	v_mfma_f32_16x16x32_bf16 v[18:21], v[172:175], v[196:199], v[18:21]
	v_mfma_f32_16x16x32_bf16 v[6:9], v[164:167], v[204:207], v[6:9]
	v_mfma_f32_16x16x32_bf16 v[2:5], v[172:175], v[204:207], v[2:5]
	s_setprio 0
	s_barrier
; #define PG8_STAGE(bufoff, gbase, voff) do { _Pragma("unroll") for (int _i = 0; _i < 2; ++_i) \
;         __builtin_amdgcn_global_load_lds((const unsigned*)((const char*)(gbase) + (voff)[_i]), (LAS unsigned*)(lds + (bufoff) + ldsw + _i * 8192), 16, 0, 0); } while (0)
; #define PG8_LDA(dst, b, h) do { _Pragma("unroll") for (int m = 0; m < 4; ++m) _Pragma("unroll") for (int k = 0; k < 2; ++k) dst[m][k] = *(const LAS bf16x8*)(lds + PG8_SA(b, h) + aoff + m * 2048 + k * 1024); } while (0)
; #define PG8_LDB(dst, b, h) do { _Pragma("unroll") for (int n = 0; n < 2; ++n) _Pragma("unroll") for (int k = 0; k < 2; ++k) dst[n][k] = *(const LAS bf16x8*)(lds + PG8_SB(b, h) + boff + n * 2048 + k * 1024); } while (0)
; #define PG8_MMA(ai, bj, At, Bt) do { __builtin_amdgcn_s_setprio(1); _Pragma("unroll") for (int m = 0; m < 4; ++m) _Pragma("unroll") for (int n = 0; n < 2; ++n) _Pragma("unroll") for (int k = 0; k < 2; ++k) \
;         acc[ai][bj][m][n] = __builtin_amdgcn_mfma_f32_16x16x32_bf16(Bt[n][k], At[m][k], acc[ai][bj][m][n], 0, 0, 0); __builtin_amdgcn_s_setprio(0); } while (0)
; #define PG8_WAIT_V(n) asm volatile("s_waitcnt vmcnt(" #n ")" ::: "memory")
; #define PG8_WAIT_L(n) asm volatile("s_waitcnt lgkmcnt(" #n ")" ::: "memory")
; #define PG8_BAR __builtin_amdgcn_s_barrier()
; #define PG8_SCHED __builtin_amdgcn_sched_barrier(0)
; template <class Epi, bool ALIGN_EPI = true, class Sched = StaticOrder>
; __device__ __forceinline__ void gemm_phase(LAS unsigned char* lds, const Gemm g, const Sched& S, const Epi& E) {
;     ...
;             PG8_LDB(B0, 1, 0); PG8_LDB(B1, 1, 1); PG8_SCHED; PG8_LDA(At, 1, 0); PG8_STAGE(PG8_SA(0, 1), a2 + hstepA, voffA);
;             PG8_WAIT_V(8); PG8_WAIT_L(0); PG8_BAR; PG8_MMA(0, 0, At, B0); PG8_MMA(0, 1, At, B1); PG8_BAR; PG8_SCHED;
	s_mov_b32 m0, s26
	s_nop 0
	global_load_lds_dwordx4 v[220:221], off
	s_mov_b32 m0, s27
	s_nop 0
	global_load_lds_dwordx4 v[222:223], off
	s_add_i32 s51, 0, 0x18000
	s_add_i32 s52, 0, 0x1c000
	v_add_u32_e32 v156, s51, v145
	v_add_u32_e32 v172, s52, v145
	ds_read_b128 v[140:143], v156
	ds_read_b128 v[148:151], v156 offset:1024
	ds_read_b128 v[152:155], v156 offset:2048
	ds_read_b128 v[156:159], v156 offset:3072
	ds_read_b128 v[160:163], v172
	ds_read_b128 v[164:167], v172 offset:1024
	ds_read_b128 v[168:171], v172 offset:2048
	ds_read_b128 v[172:175], v172 offset:3072
	s_add_u32 s36, s36, 0x1f0000
	s_addc_u32 s37, s37, 0
	s_mov_b32 m0, s38
	v_lshl_add_u64 v[224:225], s[36:37], 0, v[130:131]
	ds_read_b128 v[176:179], v147 offset:32768
	ds_read_b128 v[180:183], v147 offset:33792
	ds_read_b128 v[184:187], v147 offset:34816
	ds_read_b128 v[188:191], v147 offset:35840
	ds_read_b128 v[192:195], v147 offset:36864
	ds_read_b128 v[196:199], v147 offset:37888
	ds_read_b128 v[200:203], v147 offset:38912
	ds_read_b128 v[204:207], v147 offset:39936
	global_load_lds_dwordx4 v[224:225], off
	v_lshl_add_u64 v[224:225], s[36:37], 0, v[132:133]
	s_mov_b32 m0, s39
	s_nop 0
	global_load_lds_dwordx4 v[224:225], off
	s_waitcnt vmcnt(8)
	s_waitcnt lgkmcnt(0)
	s_barrier
	s_setprio 1
	s_waitcnt lgkmcnt(0)
	v_mfma_f32_16x16x32_bf16 v[126:129], v[140:143], v[176:179], v[126:129]
	v_mfma_f32_16x16x32_bf16 v[122:125], v[152:155], v[176:179], v[122:125]
	v_mfma_f32_16x16x32_bf16 v[110:113], v[140:143], v[184:187], v[110:113]
	v_mfma_f32_16x16x32_bf16 v[106:109], v[152:155], v[184:187], v[106:109]
	v_mfma_f32_16x16x32_bf16 v[94:97], v[140:143], v[192:195], v[94:97]
	v_mfma_f32_16x16x32_bf16 v[90:93], v[152:155], v[192:195], v[90:93]
	v_mfma_f32_16x16x32_bf16 v[78:81], v[140:143], v[200:203], v[78:81]
	v_mfma_f32_16x16x32_bf16 v[74:77], v[152:155], v[200:203], v[74:77]
	v_mfma_f32_16x16x32_bf16 v[126:129], v[148:151], v[180:183], v[126:129]
	v_mfma_f32_16x16x32_bf16 v[122:125], v[156:159], v[180:183], v[122:125]
	v_mfma_f32_16x16x32_bf16 v[110:113], v[148:151], v[188:191], v[110:113]
	v_mfma_f32_16x16x32_bf16 v[106:109], v[156:159], v[188:191], v[106:109]
	v_mfma_f32_16x16x32_bf16 v[94:97], v[148:151], v[196:199], v[94:97]
	v_mfma_f32_16x16x32_bf16 v[90:93], v[156:159], v[196:199], v[90:93]
	v_mfma_f32_16x16x32_bf16 v[78:81], v[148:151], v[204:207], v[78:81]
	v_mfma_f32_16x16x32_bf16 v[74:77], v[156:159], v[204:207], v[74:77]
	s_setprio 0
	s_setprio 1
	v_mfma_f32_16x16x32_bf16 v[118:121], v[160:163], v[176:179], v[118:121]
	v_mfma_f32_16x16x32_bf16 v[114:117], v[168:171], v[176:179], v[114:117]
	v_mfma_f32_16x16x32_bf16 v[102:105], v[160:163], v[184:187], v[102:105]
	v_mfma_f32_16x16x32_bf16 v[98:101], v[168:171], v[184:187], v[98:101]
	v_mfma_f32_16x16x32_bf16 v[86:89], v[160:163], v[192:195], v[86:89]
	v_mfma_f32_16x16x32_bf16 v[82:85], v[168:171], v[192:195], v[82:85]
	v_mfma_f32_16x16x32_bf16 v[70:73], v[160:163], v[200:203], v[70:73]
	v_mfma_f32_16x16x32_bf16 v[66:69], v[168:171], v[200:203], v[66:69]
	v_mfma_f32_16x16x32_bf16 v[118:121], v[164:167], v[180:183], v[118:121]
	v_mfma_f32_16x16x32_bf16 v[114:117], v[172:175], v[180:183], v[114:117]
	v_mfma_f32_16x16x32_bf16 v[102:105], v[164:167], v[188:191], v[102:105]
	v_mfma_f32_16x16x32_bf16 v[98:101], v[172:175], v[188:191], v[98:101]
	v_mfma_f32_16x16x32_bf16 v[86:89], v[164:167], v[196:199], v[86:89]
	v_mfma_f32_16x16x32_bf16 v[82:85], v[172:175], v[196:199], v[82:85]
	v_mfma_f32_16x16x32_bf16 v[70:73], v[164:167], v[204:207], v[70:73]
	v_mfma_f32_16x16x32_bf16 v[66:69], v[172:175], v[204:207], v[66:69]
	s_setprio 0
	s_barrier
; #define PG8_STAGE(bufoff, gbase, voff) do { _Pragma("unroll") for (int _i = 0; _i < 2; ++_i) \
;         __builtin_amdgcn_global_load_lds((const unsigned*)((const char*)(gbase) + (voff)[_i]), (LAS unsigned*)(lds + (bufoff) + ldsw + _i * 8192), 16, 0, 0); } while (0)
; #define PG8_LDA(dst, b, h) do { _Pragma("unroll") for (int m = 0; m < 4; ++m) _Pragma("unroll") for (int k = 0; k < 2; ++k) dst[m][k] = *(const LAS bf16x8*)(lds + PG8_SA(b, h) + aoff + m * 2048 + k * 1024); } while (0)
; #define PG8_MMA(ai, bj, At, Bt) do { __builtin_amdgcn_s_setprio(1); _Pragma("unroll") for (int m = 0; m < 4; ++m) _Pragma("unroll") for (int n = 0; n < 2; ++n) _Pragma("unroll") for (int k = 0; k < 2; ++k) \
;         acc[ai][bj][m][n] = __builtin_amdgcn_mfma_f32_16x16x32_bf16(Bt[n][k], At[m][k], acc[ai][bj][m][n], 0, 0, 0); __builtin_amdgcn_s_setprio(0); } while (0)
; #define PG8_WAIT_V(n) asm volatile("s_waitcnt vmcnt(" #n ")" ::: "memory")
; #define PG8_WAIT_L(n) asm volatile("s_waitcnt lgkmcnt(" #n ")" ::: "memory")
; #define PG8_BAR __builtin_amdgcn_s_barrier()
; #define PG8_SCHED __builtin_amdgcn_sched_barrier(0)
; template <class Epi, bool ALIGN_EPI = true, class Sched = StaticOrder>
; __device__ __forceinline__ void gemm_phase(LAS unsigned char* lds, const Gemm g, const Sched& S, const Epi& E) {
;     ...
;             PG8_LDA(At, 1, 1); PG8_STAGE(PG8_SB(1, 0), b3, voffB); PG8_STAGE(PG8_SB(1, 1), b3 + hstepB, voffB); PG8_STAGE(PG8_SA(1, 0), a3, voffA);
;             PG8_WAIT_V(8); PG8_WAIT_L(0); PG8_BAR; PG8_MMA(1, 0, At, B0); PG8_MMA(1, 1, At, B1); PG8_BAR; PG8_SCHED;
;         }
;         if constexpr (Epi::HAS_PRE) { if (has_next) E.pre(nxt, (ui + 1) & 1); }
;         if constexpr (ALIGN_EPI) { if (wr == 0) PG8_BAR; }
	s_add_i32 s36, s51, s25
	v_lshl_add_u64 v[216:217], v[216:217], 0, s[70:71]
	s_mov_b32 m0, s36
	ds_read_b128 v[176:179], v147 offset:49152
	ds_read_b128 v[180:183], v147 offset:50176
	ds_read_b128 v[184:187], v147 offset:51200
	ds_read_b128 v[188:191], v147 offset:52224
	ds_read_b128 v[192:195], v147 offset:53248
	ds_read_b128 v[196:199], v147 offset:54272
	ds_read_b128 v[200:203], v147 offset:55296
	ds_read_b128 v[204:207], v147 offset:56320
	global_load_lds_dwordx4 v[216:217], off
	s_add_i32 m0, s36, 0x2000
	s_add_u32 s36, s64, 0x40080
	v_lshl_add_u64 v[216:217], v[218:219], 0, s[70:71]
	s_addc_u32 s37, s65, 0
	s_add_i32 s51, s52, s25
	global_load_lds_dwordx4 v[216:217], off
	v_lshl_add_u64 v[216:217], s[36:37], 0, v[0:1]
	s_mov_b32 m0, s51
	s_nop 0
	global_load_lds_dwordx4 v[216:217], off
	v_lshl_add_u64 v[216:217], s[36:37], 0, v[134:135]
	s_add_i32 m0, s51, 0x2000
	s_nop 0
	global_load_lds_dwordx4 v[216:217], off
	s_waitcnt vmcnt(6)
	s_waitcnt lgkmcnt(0)
	s_barrier
	s_setprio 1
	s_waitcnt lgkmcnt(0)
	v_mfma_f32_16x16x32_bf16 v[62:65], v[140:143], v[176:179], v[62:65]
	v_mfma_f32_16x16x32_bf16 v[58:61], v[152:155], v[176:179], v[58:61]
	v_mfma_f32_16x16x32_bf16 v[46:49], v[140:143], v[184:187], v[46:49]
	v_mfma_f32_16x16x32_bf16 v[42:45], v[152:155], v[184:187], v[42:45]
	v_mfma_f32_16x16x32_bf16 v[30:33], v[140:143], v[192:195], v[30:33]
	v_mfma_f32_16x16x32_bf16 v[26:29], v[152:155], v[192:195], v[26:29]
	v_mfma_f32_16x16x32_bf16 v[14:17], v[140:143], v[200:203], v[14:17]
	v_mfma_f32_16x16x32_bf16 v[10:13], v[152:155], v[200:203], v[10:13]
	v_mfma_f32_16x16x32_bf16 v[62:65], v[148:151], v[180:183], v[62:65]
	v_mfma_f32_16x16x32_bf16 v[58:61], v[156:159], v[180:183], v[58:61]
	v_mfma_f32_16x16x32_bf16 v[46:49], v[148:151], v[188:191], v[46:49]
	v_mfma_f32_16x16x32_bf16 v[42:45], v[156:159], v[188:191], v[42:45]
	v_mfma_f32_16x16x32_bf16 v[30:33], v[148:151], v[196:199], v[30:33]
	v_mfma_f32_16x16x32_bf16 v[26:29], v[156:159], v[196:199], v[26:29]
	v_mfma_f32_16x16x32_bf16 v[14:17], v[148:151], v[204:207], v[14:17]
	v_mfma_f32_16x16x32_bf16 v[10:13], v[156:159], v[204:207], v[10:13]
	s_setprio 0
	s_setprio 1
	v_mfma_f32_16x16x32_bf16 v[54:57], v[160:163], v[176:179], v[54:57]
	v_mfma_f32_16x16x32_bf16 v[50:53], v[168:171], v[176:179], v[50:53]
	v_mfma_f32_16x16x32_bf16 v[38:41], v[160:163], v[184:187], v[38:41]
	v_mfma_f32_16x16x32_bf16 v[34:37], v[168:171], v[184:187], v[34:37]
	v_mfma_f32_16x16x32_bf16 v[22:25], v[160:163], v[192:195], v[22:25]
	v_mfma_f32_16x16x32_bf16 v[18:21], v[168:171], v[192:195], v[18:21]
	v_mfma_f32_16x16x32_bf16 v[6:9], v[160:163], v[200:203], v[6:9]
	v_mfma_f32_16x16x32_bf16 v[2:5], v[168:171], v[200:203], v[2:5]
	v_mfma_f32_16x16x32_bf16 v[54:57], v[164:167], v[180:183], v[54:57]
	v_mfma_f32_16x16x32_bf16 v[50:53], v[172:175], v[180:183], v[50:53]
	v_mfma_f32_16x16x32_bf16 v[38:41], v[164:167], v[188:191], v[38:41]
	v_mfma_f32_16x16x32_bf16 v[34:37], v[172:175], v[188:191], v[34:37]
	v_mfma_f32_16x16x32_bf16 v[22:25], v[164:167], v[196:199], v[22:25]
	v_mfma_f32_16x16x32_bf16 v[18:21], v[172:175], v[196:199], v[18:21]
	v_mfma_f32_16x16x32_bf16 v[6:9], v[164:167], v[204:207], v[6:9]
	v_mfma_f32_16x16x32_bf16 v[2:5], v[172:175], v[204:207], v[2:5]
	s_setprio 0
	s_barrier
	s_add_i32 s50, s50, 2
	s_add_u32 s48, s48, 0x100
	s_addc_u32 s49, s49, 0
	s_cmp_gt_u32 s50, 13
	s_mov_b64 s[62:63], s[0:1]
	s_cbranch_scc0 .LBB0_338
	s_and_b64 vcc, exec, s[34:35]
	s_cbranch_vccz .LBB0_341
	s_barrier

; #define PG8_STAGE(bufoff, gbase, voff) do { _Pragma("unroll") for (int _i = 0; _i < 2; ++_i) \
;         __builtin_amdgcn_global_load_lds((const unsigned*)((const char*)(gbase) + (voff)[_i]), (LAS unsigned*)(lds + (bufoff) + ldsw + _i * 8192), 16, 0, 0); } while (0)
; #define PG8_LDA(dst, b, h) do { _Pragma("unroll") for (int m = 0; m < 4; ++m) _Pragma("unroll") for (int k = 0; k < 2; ++k) dst[m][k] = *(const LAS bf16x8*)(lds + PG8_SA(b, h) + aoff + m * 2048 + k * 1024); } while (0)
; #define PG8_LDB(dst, b, h) do { _Pragma("unroll") for (int n = 0; n < 2; ++n) _Pragma("unroll") for (int k = 0; k < 2; ++k) dst[n][k] = *(const LAS bf16x8*)(lds + PG8_SB(b, h) + boff + n * 2048 + k * 1024); } while (0)
; #define PG8_MMA(ai, bj, At, Bt) do { __builtin_amdgcn_s_setprio(1); _Pragma("unroll") for (int m = 0; m < 4; ++m) _Pragma("unroll") for (int n = 0; n < 2; ++n) _Pragma("unroll") for (int k = 0; k < 2; ++k) \
;         acc[ai][bj][m][n] = __builtin_amdgcn_mfma_f32_16x16x32_bf16(Bt[n][k], At[m][k], acc[ai][bj][m][n], 0, 0, 0); __builtin_amdgcn_s_setprio(0); } while (0)
; #define PG8_WAIT_V(n) asm volatile("s_waitcnt vmcnt(" #n ")" ::: "memory")
; #define PG8_WAIT_L(n) asm volatile("s_waitcnt lgkmcnt(" #n ")" ::: "memory")
; #define PG8_BAR __builtin_amdgcn_s_barrier()
; #define PG8_SCHED __builtin_amdgcn_sched_barrier(0)
; template <class Epi, bool ALIGN_EPI = true, class Sched = StaticOrder>
; __device__ __forceinline__ void gemm_phase(LAS unsigned char* lds, const Gemm g, const Sched& S, const Epi& E) {
;     ...
;             PG8_LDB(B0, 0, 0); PG8_LDB(B1, 0, 1); PG8_SCHED; PG8_LDA(At, 0, 0); PG8_STAGE(PG8_SA(1, 1), a1 + hstepA, voffA);
;             PG8_WAIT_V(8); PG8_WAIT_L(0); PG8_BAR; PG8_MMA(0, 0, At, B0); PG8_MMA(0, 1, At, B1); PG8_BAR; PG8_SCHED;
.LBB0_374:
	s_add_u32 s36, s58, 0xfffc0080
	s_addc_u32 s37, s59, -1
	s_add_i32 s46, 0, 0x10000
	s_cmp_eq_u32 s45, 12
	s_cselect_b32 s37, s9, s37
	s_cselect_b32 s36, s12, s36
	s_cselect_b32 s61, s7, s44
	s_cselect_b32 s60, s13, s43
	s_add_i32 s48, 0, 0x14000
	v_add_u32_e32 v160, s46, v145
	v_add_u32_e32 v176, s48, v145
	ds_read_b128 v[140:143], v160
	ds_read_b128 v[152:155], v160 offset:1024
	ds_read_b128 v[156:159], v160 offset:2048
	ds_read_b128 v[160:163], v160 offset:3072
	ds_read_b128 v[164:167], v176
	ds_read_b128 v[168:171], v176 offset:1024
	ds_read_b128 v[172:175], v176 offset:2048
	ds_read_b128 v[176:179], v176 offset:3072
	s_add_u32 s100, s58, 0xfffc0000
	s_addc_u32 s101, s59, -1
	v_lshl_add_u64 v[196:197], s[100:101], 0, v[136:137]
	s_mov_b32 m0, s38
	v_lshl_add_u64 v[190:191], s[100:101], 0, v[138:139]
	global_load_lds_dwordx4 v[196:197], off
	s_mov_b32 m0, s39
	s_nop 0
	global_load_lds_dwordx4 v[190:191], off
	v_lshl_add_u64 v[188:189], s[58:59], 0, v[136:137]
	s_add_i32 m0, s11, 0xc000
	ds_read_b128 v[180:183], v151
	ds_read_b128 v[184:187], v151 offset:1024
	ds_read_b128 v[198:201], v151 offset:2048
	ds_read_b128 v[202:205], v151 offset:3072
	ds_read_b128 v[216:219], v151 offset:4096
	ds_read_b128 v[220:223], v151 offset:5120
	ds_read_b128 v[224:227], v151 offset:6144
	ds_read_b128 v[234:237], v151 offset:7168
	global_load_lds_dwordx4 v[188:189], off
	v_lshl_add_u64 v[188:189], s[58:59], 0, v[138:139]
	s_add_i32 m0, s11, 0xe000
	s_nop 0
	global_load_lds_dwordx4 v[188:189], off
	s_cmp_lg_u32 s45, -2
	s_cbranch_scc1 .Lw8_s0p
	s_waitcnt vmcnt(24)
	s_branch .Lwj_s0p

; #define PG8_STAGE(bufoff, gbase, voff) do { _Pragma("unroll") for (int _i = 0; _i < 2; ++_i) \
;         __builtin_amdgcn_global_load_lds((const unsigned*)((const char*)(gbase) + (voff)[_i]), (LAS unsigned*)(lds + (bufoff) + ldsw + _i * 8192), 16, 0, 0); } while (0)
; #define PG8_LDA(dst, b, h) do { _Pragma("unroll") for (int m = 0; m < 4; ++m) _Pragma("unroll") for (int k = 0; k < 2; ++k) dst[m][k] = *(const LAS bf16x8*)(lds + PG8_SA(b, h) + aoff + m * 2048 + k * 1024); } while (0)
; #define PG8_MMA(ai, bj, At, Bt) do { __builtin_amdgcn_s_setprio(1); _Pragma("unroll") for (int m = 0; m < 4; ++m) _Pragma("unroll") for (int n = 0; n < 2; ++n) _Pragma("unroll") for (int k = 0; k < 2; ++k) \
;         acc[ai][bj][m][n] = __builtin_amdgcn_mfma_f32_16x16x32_bf16(Bt[n][k], At[m][k], acc[ai][bj][m][n], 0, 0, 0); __builtin_amdgcn_s_setprio(0); } while (0)
; #define PG8_WAIT_V(n) asm volatile("s_waitcnt vmcnt(" #n ")" ::: "memory")
; #define PG8_WAIT_L(n) asm volatile("s_waitcnt lgkmcnt(" #n ")" ::: "memory")
; #define PG8_BAR __builtin_amdgcn_s_barrier()
; #define PG8_SCHED __builtin_amdgcn_sched_barrier(0)
; template <class Epi, bool ALIGN_EPI = true, class Sched = StaticOrder>
; __device__ __forceinline__ void gemm_phase(LAS unsigned char* lds, const Gemm g, const Sched& S, const Epi& E) {
;     ...
;             PG8_WAIT_V(8); PG8_WAIT_L(0); PG8_BAR; PG8_MMA(0, 0, At, B0); PG8_MMA(0, 1, At, B1); PG8_BAR; PG8_SCHED;
;             PG8_LDA(At, 0, 1); PG8_STAGE(PG8_SB(0, 0), b2, voffB); PG8_STAGE(PG8_SB(0, 1), b2 + hstepB, voffB); PG8_STAGE(PG8_SA(0, 0), a2, voffA);
;             PG8_WAIT_V(8); PG8_WAIT_L(0); PG8_BAR; PG8_MMA(1, 0, At, B0); PG8_MMA(1, 1, At, B1); PG8_BAR; PG8_SCHED;
.Lwj_s0p:
	s_waitcnt lgkmcnt(0)
	s_barrier
	s_setprio 1
	s_waitcnt lgkmcnt(0)
	v_mfma_f32_16x16x32_bf16 v[126:129], v[140:143], v[180:183], v[126:129]
	v_mfma_f32_16x16x32_bf16 v[122:125], v[156:159], v[180:183], v[122:125]
	v_mfma_f32_16x16x32_bf16 v[118:121], v[140:143], v[198:201], v[118:121]
	v_mfma_f32_16x16x32_bf16 v[110:113], v[156:159], v[198:201], v[110:113]
	v_mfma_f32_16x16x32_bf16 v[102:105], v[140:143], v[216:219], v[102:105]
	v_mfma_f32_16x16x32_bf16 v[94:97], v[156:159], v[216:219], v[94:97]
	v_mfma_f32_16x16x32_bf16 v[86:89], v[140:143], v[224:227], v[86:89]
	v_mfma_f32_16x16x32_bf16 v[78:81], v[156:159], v[224:227], v[78:81]
	v_mfma_f32_16x16x32_bf16 v[126:129], v[152:155], v[184:187], v[126:129]
	v_mfma_f32_16x16x32_bf16 v[122:125], v[160:163], v[184:187], v[122:125]
	v_mfma_f32_16x16x32_bf16 v[118:121], v[152:155], v[202:205], v[118:121]
	v_mfma_f32_16x16x32_bf16 v[110:113], v[160:163], v[202:205], v[110:113]
	v_mfma_f32_16x16x32_bf16 v[102:105], v[152:155], v[220:223], v[102:105]
	v_mfma_f32_16x16x32_bf16 v[94:97], v[160:163], v[220:223], v[94:97]
	v_mfma_f32_16x16x32_bf16 v[86:89], v[152:155], v[234:237], v[86:89]
	v_mfma_f32_16x16x32_bf16 v[78:81], v[160:163], v[234:237], v[78:81]
	s_setprio 0
	s_setprio 1
	v_mfma_f32_16x16x32_bf16 v[114:117], v[164:167], v[180:183], v[114:117]
	v_mfma_f32_16x16x32_bf16 v[106:109], v[172:175], v[180:183], v[106:109]
	v_mfma_f32_16x16x32_bf16 v[98:101], v[164:167], v[198:201], v[98:101]
	v_mfma_f32_16x16x32_bf16 v[90:93], v[172:175], v[198:201], v[90:93]
	v_mfma_f32_16x16x32_bf16 v[82:85], v[164:167], v[216:219], v[82:85]
	v_mfma_f32_16x16x32_bf16 v[74:77], v[172:175], v[216:219], v[74:77]
	v_mfma_f32_16x16x32_bf16 v[70:73], v[164:167], v[224:227], v[70:73]
	v_mfma_f32_16x16x32_bf16 v[66:69], v[172:175], v[224:227], v[66:69]
	v_mfma_f32_16x16x32_bf16 v[114:117], v[168:171], v[184:187], v[114:117]
	v_mfma_f32_16x16x32_bf16 v[106:109], v[176:179], v[184:187], v[106:109]
	v_mfma_f32_16x16x32_bf16 v[98:101], v[168:171], v[202:205], v[98:101]
	v_mfma_f32_16x16x32_bf16 v[90:93], v[176:179], v[202:205], v[90:93]
	v_mfma_f32_16x16x32_bf16 v[82:85], v[168:171], v[220:223], v[82:85]
	v_mfma_f32_16x16x32_bf16 v[74:77], v[176:179], v[220:223], v[74:77]
	v_mfma_f32_16x16x32_bf16 v[70:73], v[168:171], v[234:237], v[70:73]
	v_mfma_f32_16x16x32_bf16 v[66:69], v[176:179], v[234:237], v[66:69]
	s_setprio 0
	s_barrier
	s_add_i32 s46, s46, s19
	v_lshl_add_u64 v[188:189], s[60:61], 0, v[0:1]
	s_mov_b32 m0, s46
	ds_read_b128 v[180:183], v151 offset:16384
	ds_read_b128 v[184:187], v151 offset:17408
	ds_read_b128 v[198:201], v151 offset:18432
	ds_read_b128 v[202:205], v151 offset:19456
	ds_read_b128 v[216:219], v151 offset:20480
	ds_read_b128 v[220:223], v151 offset:21504
	ds_read_b128 v[224:227], v151 offset:22528
	ds_read_b128 v[234:237], v151 offset:23552
	global_load_lds_dwordx4 v[188:189], off
	s_add_i32 m0, s46, 0x2000
	s_add_u32 s46, s60, 0x40000
	v_lshl_add_u64 v[190:191], s[60:61], 0, v[134:135]
	s_addc_u32 s47, s61, 0
	s_add_i32 s48, s48, s19
	global_load_lds_dwordx4 v[190:191], off
	v_lshl_add_u64 v[192:193], s[46:47], 0, v[0:1]
	s_mov_b32 m0, s48
	v_lshl_add_u64 v[194:195], s[36:37], 0, v[132:133]
	global_load_lds_dwordx4 v[192:193], off
	v_lshl_add_u64 v[192:193], s[46:47], 0, v[134:135]
	s_add_i32 m0, s48, 0x2000
	s_nop 0
	global_load_lds_dwordx4 v[192:193], off
	v_lshl_add_u64 v[192:193], s[36:37], 0, v[130:131]
	s_waitcnt vmcnt(6)
	s_waitcnt lgkmcnt(0)
	s_barrier
	s_setprio 1
	s_waitcnt lgkmcnt(0)
	v_mfma_f32_16x16x32_bf16 v[62:65], v[140:143], v[180:183], v[62:65]
	v_mfma_f32_16x16x32_bf16 v[58:61], v[156:159], v[180:183], v[58:61]
	v_mfma_f32_16x16x32_bf16 v[54:57], v[140:143], v[198:201], v[54:57]
	v_mfma_f32_16x16x32_bf16 v[46:49], v[156:159], v[198:201], v[46:49]
	v_mfma_f32_16x16x32_bf16 v[38:41], v[140:143], v[216:219], v[38:41]
	v_mfma_f32_16x16x32_bf16 v[30:33], v[156:159], v[216:219], v[30:33]
	v_mfma_f32_16x16x32_bf16 v[22:25], v[140:143], v[224:227], v[22:25]
	v_mfma_f32_16x16x32_bf16 v[14:17], v[156:159], v[224:227], v[14:17]
	v_mfma_f32_16x16x32_bf16 v[62:65], v[152:155], v[184:187], v[62:65]
	v_mfma_f32_16x16x32_bf16 v[58:61], v[160:163], v[184:187], v[58:61]
	v_mfma_f32_16x16x32_bf16 v[54:57], v[152:155], v[202:205], v[54:57]
	v_mfma_f32_16x16x32_bf16 v[46:49], v[160:163], v[202:205], v[46:49]
	v_mfma_f32_16x16x32_bf16 v[38:41], v[152:155], v[220:223], v[38:41]
	v_mfma_f32_16x16x32_bf16 v[30:33], v[160:163], v[220:223], v[30:33]
	v_mfma_f32_16x16x32_bf16 v[22:25], v[152:155], v[234:237], v[22:25]
	v_mfma_f32_16x16x32_bf16 v[14:17], v[160:163], v[234:237], v[14:17]
	s_setprio 0
	s_setprio 1
	v_mfma_f32_16x16x32_bf16 v[50:53], v[164:167], v[180:183], v[50:53]
	v_mfma_f32_16x16x32_bf16 v[42:45], v[172:175], v[180:183], v[42:45]
	v_mfma_f32_16x16x32_bf16 v[34:37], v[164:167], v[198:201], v[34:37]
	v_mfma_f32_16x16x32_bf16 v[26:29], v[172:175], v[198:201], v[26:29]
	v_mfma_f32_16x16x32_bf16 v[18:21], v[164:167], v[216:219], v[18:21]
	v_mfma_f32_16x16x32_bf16 v[10:13], v[172:175], v[216:219], v[10:13]
	v_mfma_f32_16x16x32_bf16 v[6:9], v[164:167], v[224:227], v[6:9]
	v_mfma_f32_16x16x32_bf16 v[2:5], v[172:175], v[224:227], v[2:5]
	v_mfma_f32_16x16x32_bf16 v[50:53], v[168:171], v[184:187], v[50:53]
	v_mfma_f32_16x16x32_bf16 v[42:45], v[176:179], v[184:187], v[42:45]
	v_mfma_f32_16x16x32_bf16 v[34:37], v[168:171], v[202:205], v[34:37]
	v_mfma_f32_16x16x32_bf16 v[26:29], v[176:179], v[202:205], v[26:29]
	v_mfma_f32_16x16x32_bf16 v[18:21], v[168:171], v[220:223], v[18:21]
	v_mfma_f32_16x16x32_bf16 v[10:13], v[176:179], v[220:223], v[10:13]
	v_mfma_f32_16x16x32_bf16 v[6:9], v[168:171], v[234:237], v[6:9]
	v_mfma_f32_16x16x32_bf16 v[2:5], v[176:179], v[234:237], v[2:5]
	s_setprio 0
	s_barrier
; #define PG8_STAGE(bufoff, gbase, voff) do { _Pragma("unroll") for (int _i = 0; _i < 2; ++_i) \
;         __builtin_amdgcn_global_load_lds((const unsigned*)((const char*)(gbase) + (voff)[_i]), (LAS unsigned*)(lds + (bufoff) + ldsw + _i * 8192), 16, 0, 0); } while (0)
; #define PG8_LDA(dst, b, h) do { _Pragma("unroll") for (int m = 0; m < 4; ++m) _Pragma("unroll") for (int k = 0; k < 2; ++k) dst[m][k] = *(const LAS bf16x8*)(lds + PG8_SA(b, h) + aoff + m * 2048 + k * 1024); } while (0)
; #define PG8_LDB(dst, b, h) do { _Pragma("unroll") for (int n = 0; n < 2; ++n) _Pragma("unroll") for (int k = 0; k < 2; ++k) dst[n][k] = *(const LAS bf16x8*)(lds + PG8_SB(b, h) + boff + n * 2048 + k * 1024); } while (0)
; #define PG8_MMA(ai, bj, At, Bt) do { __builtin_amdgcn_s_setprio(1); _Pragma("unroll") for (int m = 0; m < 4; ++m) _Pragma("unroll") for (int n = 0; n < 2; ++n) _Pragma("unroll") for (int k = 0; k < 2; ++k) \
;         acc[ai][bj][m][n] = __builtin_amdgcn_mfma_f32_16x16x32_bf16(Bt[n][k], At[m][k], acc[ai][bj][m][n], 0, 0, 0); __builtin_amdgcn_s_setprio(0); } while (0)
; #define PG8_WAIT_V(n) asm volatile("s_waitcnt vmcnt(" #n ")" ::: "memory")
; #define PG8_WAIT_L(n) asm volatile("s_waitcnt lgkmcnt(" #n ")" ::: "memory")
; #define PG8_BAR __builtin_amdgcn_s_barrier()
; #define PG8_SCHED __builtin_amdgcn_sched_barrier(0)
; template <class Epi, bool ALIGN_EPI = true, class Sched = StaticOrder>
; __device__ __forceinline__ void gemm_phase(LAS unsigned char* lds, const Gemm g, const Sched& S, const Epi& E) {
;     ...
;             PG8_LDB(B0, 1, 0); PG8_LDB(B1, 1, 1); PG8_SCHED; PG8_LDA(At, 1, 0); PG8_STAGE(PG8_SA(0, 1), a2 + hstepA, voffA);
;             PG8_WAIT_V(8); PG8_WAIT_L(0); PG8_BAR; PG8_MMA(0, 0, At, B0); PG8_MMA(0, 1, At, B1); PG8_BAR; PG8_SCHED;
;             PG8_LDA(At, 1, 1); PG8_STAGE(PG8_SB(1, 0), b3, voffB); PG8_STAGE(PG8_SB(1, 1), b3 + hstepB, voffB); PG8_STAGE(PG8_SA(1, 0), a3, voffA);
;             PG8_WAIT_V(8); PG8_WAIT_L(0); PG8_BAR; PG8_MMA(1, 0, At, B0); PG8_MMA(1, 1, At, B1); PG8_BAR; PG8_SCHED;
	s_mov_b32 m0, s11
	s_nop 0
	global_load_lds_dwordx4 v[192:193], off
	s_mov_b32 m0, s25
	s_nop 0
	global_load_lds_dwordx4 v[194:195], off
	s_add_i32 s46, 0, 0x18000
	s_add_i32 s47, 0, 0x1c000
	v_add_u32_e32 v160, s46, v145
	v_add_u32_e32 v176, s47, v145
	ds_read_b128 v[140:143], v160
	ds_read_b128 v[152:155], v160 offset:1024
	ds_read_b128 v[156:159], v160 offset:2048
	ds_read_b128 v[160:163], v160 offset:3072
	ds_read_b128 v[164:167], v176
	ds_read_b128 v[168:171], v176 offset:1024
	ds_read_b128 v[172:175], v176 offset:2048
	ds_read_b128 v[176:179], v176 offset:3072
	s_add_u32 s36, s36, 0x40000
	s_addc_u32 s37, s37, 0
	s_mov_b32 m0, s26
	v_lshl_add_u64 v[196:197], s[36:37], 0, v[130:131]
	ds_read_b128 v[180:183], v151 offset:32768
	ds_read_b128 v[184:187], v151 offset:33792
	ds_read_b128 v[198:201], v151 offset:34816
	ds_read_b128 v[202:205], v151 offset:35840
	ds_read_b128 v[216:219], v151 offset:36864
	ds_read_b128 v[220:223], v151 offset:37888
	ds_read_b128 v[224:227], v151 offset:38912
	ds_read_b128 v[234:237], v151 offset:39936
	global_load_lds_dwordx4 v[196:197], off
	v_lshl_add_u64 v[196:197], s[36:37], 0, v[132:133]
	s_mov_b32 m0, s27
	s_nop 0
	global_load_lds_dwordx4 v[196:197], off
	s_waitcnt vmcnt(8)
	s_waitcnt lgkmcnt(0)
	s_barrier
	s_setprio 1
	s_waitcnt lgkmcnt(0)
	v_mfma_f32_16x16x32_bf16 v[126:129], v[140:143], v[180:183], v[126:129]
	v_mfma_f32_16x16x32_bf16 v[122:125], v[156:159], v[180:183], v[122:125]
	v_mfma_f32_16x16x32_bf16 v[118:121], v[140:143], v[198:201], v[118:121]
	v_mfma_f32_16x16x32_bf16 v[110:113], v[156:159], v[198:201], v[110:113]
	v_mfma_f32_16x16x32_bf16 v[102:105], v[140:143], v[216:219], v[102:105]
	v_mfma_f32_16x16x32_bf16 v[94:97], v[156:159], v[216:219], v[94:97]
	v_mfma_f32_16x16x32_bf16 v[86:89], v[140:143], v[224:227], v[86:89]
	v_mfma_f32_16x16x32_bf16 v[78:81], v[156:159], v[224:227], v[78:81]
	v_mfma_f32_16x16x32_bf16 v[126:129], v[152:155], v[184:187], v[126:129]
	v_mfma_f32_16x16x32_bf16 v[122:125], v[160:163], v[184:187], v[122:125]
	v_mfma_f32_16x16x32_bf16 v[118:121], v[152:155], v[202:205], v[118:121]
	v_mfma_f32_16x16x32_bf16 v[110:113], v[160:163], v[202:205], v[110:113]
	v_mfma_f32_16x16x32_bf16 v[102:105], v[152:155], v[220:223], v[102:105]
	v_mfma_f32_16x16x32_bf16 v[94:97], v[160:163], v[220:223], v[94:97]
	v_mfma_f32_16x16x32_bf16 v[86:89], v[152:155], v[234:237], v[86:89]
	v_mfma_f32_16x16x32_bf16 v[78:81], v[160:163], v[234:237], v[78:81]
	s_setprio 0
	s_setprio 1
	v_mfma_f32_16x16x32_bf16 v[114:117], v[164:167], v[180:183], v[114:117]
	v_mfma_f32_16x16x32_bf16 v[106:109], v[172:175], v[180:183], v[106:109]
	v_mfma_f32_16x16x32_bf16 v[98:101], v[164:167], v[198:201], v[98:101]
	v_mfma_f32_16x16x32_bf16 v[90:93], v[172:175], v[198:201], v[90:93]
	v_mfma_f32_16x16x32_bf16 v[82:85], v[164:167], v[216:219], v[82:85]
	v_mfma_f32_16x16x32_bf16 v[74:77], v[172:175], v[216:219], v[74:77]
	v_mfma_f32_16x16x32_bf16 v[70:73], v[164:167], v[224:227], v[70:73]
	v_mfma_f32_16x16x32_bf16 v[66:69], v[172:175], v[224:227], v[66:69]
	v_mfma_f32_16x16x32_bf16 v[114:117], v[168:171], v[184:187], v[114:117]
	v_mfma_f32_16x16x32_bf16 v[106:109], v[176:179], v[184:187], v[106:109]
	v_mfma_f32_16x16x32_bf16 v[98:101], v[168:171], v[202:205], v[98:101]
	v_mfma_f32_16x16x32_bf16 v[90:93], v[176:179], v[202:205], v[90:93]
	v_mfma_f32_16x16x32_bf16 v[82:85], v[168:171], v[220:223], v[82:85]
	v_mfma_f32_16x16x32_bf16 v[74:77], v[176:179], v[220:223], v[74:77]
	v_mfma_f32_16x16x32_bf16 v[70:73], v[168:171], v[234:237], v[70:73]
	v_mfma_f32_16x16x32_bf16 v[66:69], v[176:179], v[234:237], v[66:69]
	s_setprio 0
	s_barrier
	s_add_i32 s36, s46, s19
	v_lshl_add_u64 v[188:189], v[188:189], 0, s[70:71]
	s_mov_b32 m0, s36
	ds_read_b128 v[180:183], v151 offset:49152
	ds_read_b128 v[184:187], v151 offset:50176
	ds_read_b128 v[198:201], v151 offset:51200
	ds_read_b128 v[202:205], v151 offset:52224
	ds_read_b128 v[216:219], v151 offset:53248
	ds_read_b128 v[220:223], v151 offset:54272
	ds_read_b128 v[224:227], v151 offset:55296
	ds_read_b128 v[234:237], v151 offset:56320
	global_load_lds_dwordx4 v[188:189], off
	s_add_i32 m0, s36, 0x2000
	s_add_u32 s36, s60, 0x40080
	v_lshl_add_u64 v[188:189], v[190:191], 0, s[70:71]
	s_addc_u32 s37, s61, 0
	s_add_i32 s46, s47, s19
	global_load_lds_dwordx4 v[188:189], off
	v_lshl_add_u64 v[188:189], s[36:37], 0, v[0:1]
	s_mov_b32 m0, s46
	s_nop 0
	global_load_lds_dwordx4 v[188:189], off
	v_lshl_add_u64 v[188:189], s[36:37], 0, v[134:135]
	s_add_i32 m0, s46, 0x2000
	s_nop 0
	global_load_lds_dwordx4 v[188:189], off
	s_waitcnt vmcnt(6)
	s_waitcnt lgkmcnt(0)
	s_barrier
; #define PG8_MMA(ai, bj, At, Bt) do { __builtin_amdgcn_s_setprio(1); _Pragma("unroll") for (int m = 0; m < 4; ++m) _Pragma("unroll") for (int n = 0; n < 2; ++n) _Pragma("unroll") for (int k = 0; k < 2; ++k) \
;         acc[ai][bj][m][n] = __builtin_amdgcn_mfma_f32_16x16x32_bf16(Bt[n][k], At[m][k], acc[ai][bj][m][n], 0, 0, 0); __builtin_amdgcn_s_setprio(0); } while (0)
; #define PG8_WAIT_V(n) asm volatile("s_waitcnt vmcnt(" #n ")" ::: "memory")
; #define PG8_WAIT_L(n) asm volatile("s_waitcnt lgkmcnt(" #n ")" ::: "memory")
; #define PG8_BAR __builtin_amdgcn_s_barrier()
; #define PG8_SCHED __builtin_amdgcn_sched_barrier(0)
; template <class Epi, bool ALIGN_EPI = true, class Sched = StaticOrder>
; __device__ __forceinline__ void gemm_phase(LAS unsigned char* lds, const Gemm g, const Sched& S, const Epi& E) {
;     ...
;             PG8_WAIT_V(8); PG8_WAIT_L(0); PG8_BAR; PG8_MMA(1, 0, At, B0); PG8_MMA(1, 1, At, B1); PG8_BAR; PG8_SCHED;
;         }
;         if constexpr (Epi::HAS_PRE) { if (has_next) E.pre(nxt, (ui + 1) & 1); }
;     __device__ __forceinline__ void pre(const Unit& u, int buf) const {
;         int t = threadIdx.x; asm volatile("" : "+v"(t));
;         if (t < 256) { const f32x4* sp = (const f32x4*)(ssp + (size_t)(u.pm * BM + t) * 16);
;             const f32x4 s4 = (sp[0] + sp[1]) + (sp[2] + sp[3]);
;             stash[buf * 256 + t] = __builtin_amdgcn_rsqf(((s4[0] + s4[1]) + (s4[2] + s4[3])) * (1.f / 1024.f) + EPS); }
;     }
	s_setprio 1
	s_waitcnt lgkmcnt(0)
	v_mfma_f32_16x16x32_bf16 v[62:65], v[140:143], v[180:183], v[62:65]
	v_mfma_f32_16x16x32_bf16 v[58:61], v[156:159], v[180:183], v[58:61]
	v_mfma_f32_16x16x32_bf16 v[54:57], v[140:143], v[198:201], v[54:57]
	v_mfma_f32_16x16x32_bf16 v[46:49], v[156:159], v[198:201], v[46:49]
	v_mfma_f32_16x16x32_bf16 v[38:41], v[140:143], v[216:219], v[38:41]
	v_mfma_f32_16x16x32_bf16 v[30:33], v[156:159], v[216:219], v[30:33]
	v_mfma_f32_16x16x32_bf16 v[22:25], v[140:143], v[224:227], v[22:25]
	v_mfma_f32_16x16x32_bf16 v[14:17], v[156:159], v[224:227], v[14:17]
	v_mfma_f32_16x16x32_bf16 v[62:65], v[152:155], v[184:187], v[62:65]
	v_mfma_f32_16x16x32_bf16 v[58:61], v[160:163], v[184:187], v[58:61]
	v_mfma_f32_16x16x32_bf16 v[54:57], v[152:155], v[202:205], v[54:57]
	v_mfma_f32_16x16x32_bf16 v[46:49], v[160:163], v[202:205], v[46:49]
	v_mfma_f32_16x16x32_bf16 v[38:41], v[152:155], v[220:223], v[38:41]
	v_mfma_f32_16x16x32_bf16 v[30:33], v[160:163], v[220:223], v[30:33]
	v_mfma_f32_16x16x32_bf16 v[22:25], v[152:155], v[234:237], v[22:25]
	v_mfma_f32_16x16x32_bf16 v[14:17], v[160:163], v[234:237], v[14:17]
	s_setprio 0
	s_setprio 1
	v_mfma_f32_16x16x32_bf16 v[50:53], v[164:167], v[180:183], v[50:53]
	v_mfma_f32_16x16x32_bf16 v[42:45], v[172:175], v[180:183], v[42:45]
	v_mfma_f32_16x16x32_bf16 v[34:37], v[164:167], v[198:201], v[34:37]
	v_mfma_f32_16x16x32_bf16 v[26:29], v[172:175], v[198:201], v[26:29]
	v_mfma_f32_16x16x32_bf16 v[18:21], v[164:167], v[216:219], v[18:21]
	v_mfma_f32_16x16x32_bf16 v[10:13], v[172:175], v[216:219], v[10:13]
	v_mfma_f32_16x16x32_bf16 v[6:9], v[164:167], v[224:227], v[6:9]
	v_mfma_f32_16x16x32_bf16 v[2:5], v[172:175], v[224:227], v[2:5]
	v_mfma_f32_16x16x32_bf16 v[50:53], v[168:171], v[184:187], v[50:53]
	v_mfma_f32_16x16x32_bf16 v[42:45], v[176:179], v[184:187], v[42:45]
	v_mfma_f32_16x16x32_bf16 v[34:37], v[168:171], v[202:205], v[34:37]
	v_mfma_f32_16x16x32_bf16 v[26:29], v[176:179], v[202:205], v[26:29]
	v_mfma_f32_16x16x32_bf16 v[18:21], v[168:171], v[220:223], v[18:21]
	v_mfma_f32_16x16x32_bf16 v[10:13], v[176:179], v[220:223], v[10:13]
	v_mfma_f32_16x16x32_bf16 v[6:9], v[168:171], v[234:237], v[6:9]
	v_mfma_f32_16x16x32_bf16 v[2:5], v[176:179], v[234:237], v[2:5]
	s_setprio 0
	s_barrier
	s_add_i32 s45, s45, 2
	s_add_u32 s58, s58, 0x100
	s_addc_u32 s59, s59, 0
	s_add_u32 s43, s43, 0x100
	s_addc_u32 s44, s44, 0
	s_cmp_gt_u32 s45, 13
	s_cbranch_scc0 .LBB0_374
	s_and_b64 vcc, exec, s[0:1]
	s_cbranch_vccz .LBB0_379
	v_mov_b32_e32 v140, v208
	s_nop 0
	v_cmp_gt_i32_e32 vcc, s78, v140
	s_and_saveexec_b64 s[12:13], vcc
	s_cbranch_execz .LBB0_378
	v_lshl_add_u32 v142, s8, 8, v140
	v_ashrrev_i32_e32 v143, 31, v142
	v_lshlrev_b64 v[142:143], 6, v[142:143]
	v_lshl_add_u64 v[142:143], s[82:83], 0, v[142:143]
	global_load_dwordx4 v[152:155], v[142:143], off
	global_load_dwordx4 v[156:159], v[142:143], off offset:16
	global_load_dwordx4 v[160:163], v[142:143], off offset:32
	global_load_dwordx4 v[164:167], v[142:143], off offset:48
	s_lshl_b32 s7, s41, 10
	s_and_b32 s7, s7, 0x400
	s_add_i32 s7, s7, 0
	v_lshl_add_u32 v140, v140, 2, s7
	v_add_u32_e32 v140, 0x20600, v140
	s_waitcnt vmcnt(0)
	v_pk_add_f32 v[142:143], v[154:155], v[158:159]
	v_pk_add_f32 v[152:153], v[152:153], v[156:157]
	v_pk_add_f32 v[154:155], v[162:163], v[166:167]
	v_pk_add_f32 v[156:157], v[160:161], v[164:165]
	v_pk_add_f32 v[142:143], v[142:143], v[154:155]
	v_pk_add_f32 v[152:153], v[152:153], v[156:157]
	s_nop 0
	v_pk_mov_b32 v[154:155], v[152:153], v[142:143] op_sel:[1,0]
	v_mov_b32_e32 v153, v143
	v_pk_add_f32 v[142:143], v[154:155], v[152:153]
	s_nop 0
	v_add_f32_e32 v141, v142, v143
	v_fmamk_f32 v141, v141, 0x3a800000, v209
	v_rsq_f32_e32 v141, v141
	ds_write_b32 v140, v141
